# grid syncs 2-8: two-level barrier with separate arrival (per group of 32 + top) and release words, each workgroup polls only its group's release word
# speedup vs baseline: 1.0333x; 1.0333x over previous
; __global__ void __launch_bounds__(512, 2) hymba_fwd(Params p0) {
;     extern __shared__ __attribute__((aligned(16))) unsigned char smem[];
;     cg::grid_group grid = cg::this_grid();
;     ...
;     for (int phx = p0.ph_lo; phx < p0.ph_hi + (DUP_PHASE >= 0 ? 1 : 0); ++phx) {
;         const int ph = (DUP_PHASE >= 0 && phx > DUP_PHASE) ? phx - 1 : phx;
;         Params p = p0;
;         { size_t z = 0; asm volatile("" : "+s"(z)); p.ws = p0.ws + z; p.out = p0.out + z; }
.LBB0_1:
	s_load_dword s7, s[0:1], 0xf0
	s_load_dwordx4 s[8:11], s[0:1], 0xd8
	s_add_u32 s2, s0, 0xf0
	s_addc_u32 s3, s1, 0
	v_writelane_b32 v254, s2, 3
	v_and_b32_e32 v151, 0x3ff, v0
	v_and_b32_e32 v4, 0x3fffffff, v0
	v_writelane_b32 v254, s3, 4
	s_waitcnt lgkmcnt(0)
	s_abs_i32 s2, s7
	v_cvt_f32_u32_e32 v1, s2
	s_ashr_i32 s3, s7, 31
	v_writelane_b32 v254, s3, 5
	s_lshl_b32 s3, s7, 3
	v_rcp_iflag_f32_e32 v1, v1
	v_writelane_b32 v254, s3, 6
	s_sub_i32 s3, 0, s2
	s_lshl_b32 s47, s7, 9
	v_mul_f32_e32 v0, 0x4f7ffffe, v1
	v_cvt_u32_f32_e32 v0, v0
	v_mov_b32_e32 v149, 0
	v_mov_b32_e32 v152, 1.0
	v_mbcnt_lo_u32_b32 v205, -1, 0
	v_readfirstlane_b32 s4, v0
	s_mul_i32 s3, s3, s4
	s_mul_hi_u32 s3, s4, s3
	s_add_i32 s4, s4, s3
	s_mul_hi_u32 s3, s4, 0x65c
	s_mul_i32 s3, s3, s2
	s_sub_i32 s3, 0x65c, s3
	s_sub_i32 s6, s3, s2
	s_cmp_ge_u32 s3, s2
	s_cselect_b32 s3, s6, s3
	s_sub_i32 s6, s3, s2
	s_cmp_ge_u32 s3, s2
	s_cselect_b32 s3, s6, s3
	s_cmp_lg_u32 s3, 0
	s_cselect_b64 s[12:13], -1, 0
	v_writelane_b32 v254, s12, 7
	s_mul_hi_u32 s5, s4, 0x128
	s_mul_i32 s5, s5, s2
	v_writelane_b32 v254, s13, 8
	v_writelane_b32 v254, s3, 9
	s_sub_i32 s3, s7, s3
	v_writelane_b32 v254, s3, 10
	s_sub_i32 s3, 0x128, s5
	s_sub_i32 s5, s3, s2
	s_cmp_ge_u32 s3, s2
	s_cselect_b32 s3, s5, s3
	s_sub_i32 s5, s3, s2
	s_cmp_ge_u32 s3, s2
	s_cselect_b32 s3, s5, s3
	s_cmp_lg_u32 s3, 0
	s_cselect_b64 s[12:13], -1, 0
	v_writelane_b32 v254, s12, 11
	s_mov_b32 s91, 0x42a00000
	v_mov_b32_e32 v202, 0x358637bd
	v_writelane_b32 v254, s13, 12
	v_writelane_b32 v254, s3, 13
	s_sub_i32 s3, s7, s3
	v_writelane_b32 v254, s3, 14
	s_mul_hi_u32 s3, s4, 0x637
	s_mul_i32 s3, s3, s2
	s_sub_i32 s3, 0x637, s3
	s_sub_i32 s4, s3, s2
	s_cmp_ge_u32 s3, s2
	s_cselect_b32 s3, s4, s3
	s_sub_i32 s4, s3, s2
	s_cmp_ge_u32 s3, s2
	s_cselect_b32 s2, s4, s3
	s_cmp_lg_u32 s2, 0
	s_cselect_b64 s[4:5], -1, 0
	v_writelane_b32 v254, s4, 15
	v_mov_b32_e32 v150, 0x3ecc95a3
	v_mov_b32_e32 v203, 0x154ba000
	v_writelane_b32 v254, s5, 16
	v_writelane_b32 v254, s2, 17
	s_sub_i32 s2, s7, s2
	v_writelane_b32 v254, s2, 18
	s_add_u32 s2, s10, 0xec00000
	v_writelane_b32 v254, s2, 19
	s_addc_u32 s2, s11, 0
	s_bitcmp1_b32 s7, 0
	v_writelane_b32 v254, s2, 20
	s_cselect_b64 s[2:3], -1, 0
	v_writelane_b32 v254, s2, 21
	v_mov_b32_e32 v204, 1
	v_mov_b64_e32 v[154:155], 0x128
	v_writelane_b32 v254, s3, 22
	s_add_u32 s2, s10, 0xa200000
	v_writelane_b32 v254, s2, 23
	s_addc_u32 s2, s11, 0
	v_writelane_b32 v254, s2, 24
	s_add_u32 s2, s8, 0x543a180
	v_writelane_b32 v254, s2, 25
	v_writelane_b32 v254, s8, 26
	s_addc_u32 s2, s9, 0
	v_mov_b64_e32 v[156:157], 0x127
	v_writelane_b32 v254, s9, 27
	v_writelane_b32 v254, s10, 28
	v_writelane_b32 v254, s11, 29
	v_writelane_b32 v254, s2, 30
	v_writelane_b32 v254, s7, 31
	s_lshl_b32 s2, s7, 14
	v_writelane_b32 v254, s2, 32
	s_add_i32 s2, 0, 0x23d00
	v_writelane_b32 v254, s2, 33
	s_add_i32 s2, 0, 0x22c00
	v_writelane_b32 v254, s2, 34
	v_cmp_eq_u32_e64 s[2:3], 0, v4
	s_load_dwordx4 s[4:7], s[0:1], 0xc0
	v_mbcnt_hi_u32_b32 v206, -1, v205
	v_writelane_b32 v254, s2, 35
	v_mov_b32_e32 v207, 0x240e
	v_mov_b64_e32 v[158:159], 0x65b
	v_writelane_b32 v254, s3, 36
	s_load_dwordx2 s[2:3], s[0:1], 0xd0
	v_mov_b64_e32 v[160:161], 0x65c
	v_mov_b32_e32 v208, 0x2005
	v_mov_b32_e32 v209, 0x7fd
	v_mov_b32_e32 v0, v149
	s_waitcnt lgkmcnt(0)
	v_writelane_b32 v254, s2, 37
	v_mov_b32_e32 v1, v149
	v_mov_b32_e32 v2, v149
	v_writelane_b32 v254, s3, 38
	v_writelane_b32 v254, s4, 39
	v_mov_b32_e32 v3, v149
	v_mov_b32_e32 v162, 0x3f317218
	v_writelane_b32 v254, s5, 40
	v_writelane_b32 v254, s6, 41
	v_writelane_b32 v254, s7, 42
	s_load_dwordx16 s[4:19], s[0:1], 0x0
	v_mov_b32_e32 v210, 0x7f800000
	v_mov_b32_e32 v211, 0x7fc00000
	v_mov_b32_e32 v212, 0xff800000
	v_bfrev_b32_e32 v213, 0.5
	s_waitcnt lgkmcnt(0)
	v_writelane_b32 v254, s4, 43
	v_mov_b32_e32 v164, 1.0
	v_mov_b32_e32 v165, v152
	v_writelane_b32 v254, s5, 44
	v_writelane_b32 v254, s6, 45
	v_writelane_b32 v254, s7, 46
	v_writelane_b32 v254, s8, 47
	v_writelane_b32 v254, s9, 48
	v_writelane_b32 v254, s10, 49
	v_writelane_b32 v254, s11, 50
	v_writelane_b32 v254, s12, 51
	v_writelane_b32 v254, s13, 52
	v_writelane_b32 v254, s14, 53
	v_writelane_b32 v254, s15, 54
	v_writelane_b32 v254, s16, 55
	v_writelane_b32 v254, s17, 56
	v_writelane_b32 v254, s18, 57
	v_writelane_b32 v254, s19, 58
	s_load_dwordx16 s[4:19], s[0:1], 0x40
	v_mov_b64_e32 v[166:167], 0x636
	v_mov_b64_e32 v[168:169], 0x637
	s_movk_i32 s45, 0x5600
	s_add_i32 s49, 0, 0x1dc00
	s_waitcnt lgkmcnt(0)
	v_writelane_b32 v254, s4, 59
	s_add_i32 s51, 0, 0x11000
	s_add_i32 s53, 0, 0x19800
	v_writelane_b32 v255, s9, 0
	v_writelane_b32 v255, s10, 1
	v_writelane_b32 v255, s11, 2
	v_writelane_b32 v255, s12, 3
	v_writelane_b32 v255, s13, 4
	v_writelane_b32 v255, s14, 5
	v_writelane_b32 v255, s15, 6
	v_writelane_b32 v254, s5, 60
	v_writelane_b32 v255, s16, 7
	v_writelane_b32 v254, s6, 61
	v_writelane_b32 v255, s17, 8
	v_writelane_b32 v254, s7, 62
	v_writelane_b32 v255, s18, 9
	v_writelane_b32 v254, s8, 63
	v_writelane_b32 v255, s19, 10
	s_load_dwordx16 s[4:19], s[0:1], 0x80
	s_movk_i32 s55, 0x110
	s_mov_b32 s97, 0
	s_mov_b64 s[34:35], 0x80
	s_mov_b32 s90, 0x3db504f3
	s_waitcnt lgkmcnt(0)
	v_writelane_b32 v255, s4, 11
	s_mov_b32 s50, s47
	s_nop 0
	v_writelane_b32 v255, s5, 12
	v_writelane_b32 v255, s6, 13
	v_writelane_b32 v255, s7, 14
	v_writelane_b32 v255, s8, 15
	v_writelane_b32 v255, s9, 16
	v_writelane_b32 v255, s10, 17
	v_writelane_b32 v255, s11, 18
	v_writelane_b32 v255, s12, 19
	v_writelane_b32 v255, s13, 20
	v_writelane_b32 v255, s14, 21
	v_writelane_b32 v255, s15, 22
	v_writelane_b32 v255, s16, 23
	v_writelane_b32 v255, s17, 24
	v_writelane_b32 v255, s18, 25
	v_writelane_b32 v255, s19, 26
	s_mov_b32 s2, 0
	s_nop 0
	v_writelane_b32 v255, s2, 61
	v_writelane_b32 v255, s2, 63
	s_movk_i32 s2, 0xb0
	s_nop 0
	v_writelane_b32 v254, s2, 9
	s_movk_i32 s2, 0x50
	s_nop 0
	v_writelane_b32 v254, s2, 10
	s_branch .LBB0_5

; __global__ void __launch_bounds__(512, 2) hymba_fwd(Params p0) {
;     ...
;         if (phx + 1 < p0.ph_hi + (DUP_PHASE >= 0 ? 1 : 0)) grid.sync();
.LBB0_952:
	v_readlane_b32 s2, v254, 3
	v_readlane_b32 s3, v254, 4
	buffer_wbl2 sc1
	s_load_dwordx2 s[8:9], s[2:3], 0x58
	v_readlane_b32 s4, v254, 28
	v_readlane_b32 s5, v254, 29
	v_readlane_b32 s6, v254, 1
	v_readlane_b32 s7, v254, 0
	s_add_u32 s10, s4, 0x229f2000
	s_addc_u32 s11, s5, 0
	s_and_b32 s7, s7, 7
	s_lshl_b32 s7, s7, 8
	s_add_u32 s12, s10, s7
	s_addc_u32 s13, s11, 0
	s_cmp_lg_u32 s6, 1
	s_cbranch_scc1 .Lgsync2
	global_atomic_and v149, v149, s[12:13] offset:256
	global_atomic_and v149, v149, s[12:13] offset:2560
	global_atomic_and v149, v149, s[10:11] offset:2304
	s_waitcnt lgkmcnt(0)
	s_mov_b64 s[2:3], s[8:9]
	s_branch .Lgsync_own_word
.Lgsync2:
	v_readlane_b32 s6, v255, 63
	s_waitcnt vmcnt(0) lgkmcnt(0)
	s_add_i32 s6, s6, 1
	v_mov_b32_e32 v4, 1
	v_writelane_b32 v255, s6, 63
	global_atomic_add v5, v149, v4, s[12:13] offset:256 sc0
	s_waitcnt vmcnt(0)
	v_readfirstlane_b32 s7, v5
	s_lshl_b32 s4, s6, 5
	s_add_i32 s7, s7, 1
	s_cmp_lg_u32 s7, s4
	s_cbranch_scc1 .Lgsync2_poll
	global_atomic_add v5, v149, v4, s[10:11] offset:2304 sc0
	s_waitcnt vmcnt(0)
	v_readfirstlane_b32 s7, v5
	s_lshl_b32 s4, s6, 3
	s_add_i32 s7, s7, 1
	s_cmp_lg_u32 s7, s4
	s_cbranch_scc1 .Lgsync2_poll
	s_add_u32 s4, s10, 0xa00
	s_addc_u32 s5, s11, 0
	global_atomic_add v149, v4, s[4:5]
	global_atomic_add v149, v4, s[4:5] offset:256
	global_atomic_add v149, v4, s[4:5] offset:512
	global_atomic_add v149, v4, s[4:5] offset:768
	global_atomic_add v149, v4, s[4:5] offset:1024
	global_atomic_add v149, v4, s[4:5] offset:1280
	global_atomic_add v149, v4, s[4:5] offset:1536
	global_atomic_add v149, v4, s[4:5] offset:1792
.Lgsync2_poll:
	s_mov_b32 s7, 0
.Lgsync2_loop:
	global_load_dword v5, v149, s[12:13] offset:2560 sc1
	s_waitcnt vmcnt(0)
	v_readfirstlane_b32 s4, v5
	s_cmp_ge_u32 s4, s6
	s_cbranch_scc1 .Lgsync_spin_cap
	s_add_i32 s7, s7, 1
	s_cmp_ge_u32 s7, 0x20000
	s_cbranch_scc1 .Lgsync_spin_cap
	s_sleep 1
	s_branch .Lgsync2_loop
